# wi 11/21 + P2 FFN weight conversion: 16 LDS transpose reads per item issued together with counted waits
# baseline (speedup 1.0000x reference)
.LBB0_450:
	s_waitcnt vmcnt(0)
	v_pk_mul_f32 v[82:83], v[82:83], v[120:121] op_sel_hi:[1,0]
	ds_write2_b32 v136, v82, v83 offset1:1
	v_pk_mul_f32 v[82:83], v[84:85], v[120:121] op_sel_hi:[1,0]
	ds_write2_b32 v136, v82, v83 offset0:2 offset1:3
	v_pk_mul_f32 v[82:83], v[86:87], v[120:121] op_sel:[0,1]
	v_add_u32_e32 v1, 0x420, v136
	ds_write2_b32 v1, v82, v83 offset1:1
	v_pk_mul_f32 v[84:85], v[88:89], v[120:121] op_sel:[0,1]
	v_add_u32_e32 v82, 0x428, v136
	ds_write2_b32 v82, v84, v85 offset1:1
	v_pk_mul_f32 v[84:85], v[90:91], v[122:123] op_sel_hi:[1,0]
	v_add_u32_e32 v83, 0x840, v136
	ds_write2_b32 v83, v84, v85 offset1:1
	v_pk_mul_f32 v[86:87], v[92:93], v[122:123] op_sel_hi:[1,0]
	v_add_u32_e32 v84, 0x848, v136
	ds_write2_b32 v84, v86, v87 offset1:1
	v_mov_b32_e32 v86, v123
	v_pk_mul_f32 v[88:89], v[94:95], v[86:87] op_sel_hi:[1,0]
	v_add_u32_e32 v85, 0xc60, v136
	ds_write2_b32 v85, v88, v89 offset1:1
	v_pk_mul_f32 v[88:89], v[96:97], v[86:87] op_sel_hi:[1,0]
	v_add_u32_e32 v86, 0xc68, v136
	ds_write2_b32 v86, v88, v89 offset1:1
	v_pk_mul_f32 v[88:89], v[98:99], v[124:125] op_sel_hi:[1,0]
	v_add_u32_e32 v87, 0x1080, v136
	ds_write2_b32 v87, v88, v89 offset1:1
	v_pk_mul_f32 v[90:91], v[100:101], v[124:125] op_sel_hi:[1,0]
	v_add_u32_e32 v88, 0x1088, v136
	ds_write2_b32 v88, v90, v91 offset1:1
	v_mov_b32_e32 v90, v125
	v_pk_mul_f32 v[92:93], v[102:103], v[90:91] op_sel_hi:[1,0]
	v_add_u32_e32 v89, 0x14a0, v136
	ds_write2_b32 v89, v92, v93 offset1:1
	v_pk_mul_f32 v[92:93], v[104:105], v[90:91] op_sel_hi:[1,0]
	v_add_u32_e32 v90, 0x14a8, v136
	ds_write2_b32 v90, v92, v93 offset1:1
	v_pk_mul_f32 v[92:93], v[106:107], v[126:127] op_sel_hi:[1,0]
	v_add_u32_e32 v91, 0x18c0, v136
	ds_write2_b32 v91, v92, v93 offset1:1
	v_pk_mul_f32 v[94:95], v[108:109], v[126:127] op_sel_hi:[1,0]
	v_add_u32_e32 v92, 0x18c8, v136
	ds_write2_b32 v92, v94, v95 offset1:1
	v_mov_b32_e32 v94, v127
	v_pk_mul_f32 v[96:97], v[94:95], v[110:111] op_sel_hi:[0,1]
	v_add_u32_e32 v93, 0x1ce0, v136
	ds_write2_b32 v93, v96, v97 offset1:1
	v_pk_mul_f32 v[96:97], v[94:95], v[112:113] op_sel_hi:[0,1]
	v_add_u32_e32 v94, 0x1ce8, v136
	ds_write2_b32 v94, v96, v97 offset1:1
	s_waitcnt lgkmcnt(0)
	ds_read2_b32 v[160:161], v135 offset1:33
	ds_read2_b32 v[162:163], v135 offset0:66 offset1:99
	ds_read2_b32 v[164:165], v135 offset0:132 offset1:165
	ds_read2_b32 v[166:167], v135 offset0:198 offset1:231
	ds_read2_b32 v[168:169], v135 offset0:8 offset1:41
	ds_read2_b32 v[170:171], v135 offset0:74 offset1:107
	ds_read2_b32 v[172:173], v135 offset0:140 offset1:173
	ds_read2_b32 v[174:175], v135 offset0:206 offset1:239
	ds_read2_b32 v[176:177], v135 offset0:16 offset1:49
	ds_read2_b32 v[178:179], v135 offset0:82 offset1:115
	ds_read2_b32 v[180:181], v135 offset0:148 offset1:181
	ds_read2_b32 v[182:183], v135 offset0:214 offset1:247
	ds_read2_b32 v[184:185], v135 offset0:24 offset1:57
	ds_read2_b32 v[186:187], v135 offset0:90 offset1:123
	ds_read2_b32 v[188:189], v135 offset0:156 offset1:189
	ds_read2_b32 v[190:191], v135 offset0:222 offset1:255
	s_waitcnt lgkmcnt(15)
	v_cvt_pk_bf16_f32 v96, v160, v161
	s_waitcnt lgkmcnt(14)
	v_cvt_pk_bf16_f32 v97, v162, v163
	s_waitcnt lgkmcnt(13)
	v_cvt_pk_bf16_f32 v98, v164, v165
	v_add_u32_e32 v95, s93, v114
	s_waitcnt lgkmcnt(12)
	v_cvt_pk_bf16_f32 v99, v166, v167
	v_mad_i64_i32 v[100:101], s[8:9], s28, v95, 0
	s_ashr_i32 s35, s34, 31
	v_lshl_add_u64 v[100:101], v[100:101], 1, s[30:31]
	s_lshl_b64 s[8:9], s[34:35], 1
	v_lshl_add_u64 v[100:101], v[100:101], 0, s[8:9]
	v_mov_b32_e32 v119, v117
	v_lshl_add_u64 v[100:101], v[100:101], 0, v[118:119]
	global_store_dwordx4 v[100:101], v[96:99], off
	v_add_u32_e32 v95, s93, v128
	s_and_b64 vcc, exec, s[4:5]
	s_waitcnt lgkmcnt(11)
	v_cvt_pk_bf16_f32 v96, v168, v169
	s_waitcnt lgkmcnt(10)
	v_cvt_pk_bf16_f32 v97, v170, v171
	s_waitcnt lgkmcnt(9)
	v_cvt_pk_bf16_f32 v98, v172, v173
	s_waitcnt lgkmcnt(8)
	v_cvt_pk_bf16_f32 v99, v174, v175
	v_mad_i64_i32 v[100:101], s[34:35], s28, v95, 0
	v_lshl_add_u64 v[100:101], v[100:101], 1, s[30:31]
	v_lshl_add_u64 v[100:101], v[100:101], 0, s[8:9]
	v_lshl_add_u64 v[100:101], v[100:101], 0, v[118:119]
	global_store_dwordx4 v[100:101], v[96:99], off
	v_add_u32_e32 v95, s93, v129
	s_waitcnt lgkmcnt(7)
	v_cvt_pk_bf16_f32 v96, v176, v177
	s_waitcnt lgkmcnt(6)
	v_cvt_pk_bf16_f32 v97, v178, v179
	s_waitcnt lgkmcnt(5)
	v_cvt_pk_bf16_f32 v98, v180, v181
	s_waitcnt lgkmcnt(4)
	v_cvt_pk_bf16_f32 v99, v182, v183
	v_mad_i64_i32 v[100:101], s[34:35], s28, v95, 0
	v_lshl_add_u64 v[100:101], v[100:101], 1, s[30:31]
	v_lshl_add_u64 v[100:101], v[100:101], 0, s[8:9]
	v_lshl_add_u64 v[100:101], v[100:101], 0, v[118:119]
	global_store_dwordx4 v[100:101], v[96:99], off
	v_add_u32_e32 v95, s93, v130
	s_waitcnt lgkmcnt(3)
	v_cvt_pk_bf16_f32 v96, v184, v185
	s_waitcnt lgkmcnt(2)
	v_cvt_pk_bf16_f32 v97, v186, v187
	s_waitcnt lgkmcnt(1)
	v_cvt_pk_bf16_f32 v98, v188, v189
	s_waitcnt lgkmcnt(0)
	v_cvt_pk_bf16_f32 v99, v190, v191
	v_mad_i64_i32 v[100:101], s[34:35], s28, v95, 0
	v_lshl_add_u64 v[100:101], v[100:101], 1, s[30:31]
	v_lshl_add_u64 v[100:101], v[100:101], 0, s[8:9]
	v_lshl_add_u64 v[100:101], v[100:101], 0, v[118:119]
	global_store_dwordx4 v[100:101], v[96:99], off
	s_waitcnt lgkmcnt(0)
	s_cbranch_vccnz .LBB0_452
	s_nop 0
	v_pk_mul_f32 v[96:97], v[18:19], v[2:3] op_sel_hi:[1,0]
	ds_write2_b32 v136, v96, v97 offset1:1
	v_pk_mul_f32 v[96:97], v[20:21], v[2:3] op_sel_hi:[1,0]
	ds_write2_b32 v136, v96, v97 offset0:2 offset1:3
	v_pk_mul_f32 v[96:97], v[26:27], v[2:3] op_sel:[0,1]
	ds_write2_b32 v1, v96, v97 offset1:1
	v_pk_mul_f32 v[96:97], v[28:29], v[2:3] op_sel:[0,1]
	ds_write2_b32 v82, v96, v97 offset1:1
	v_pk_mul_f32 v[96:97], v[34:35], v[4:5] op_sel_hi:[1,0]
	ds_write2_b32 v83, v96, v97 offset1:1
	v_pk_mul_f32 v[96:97], v[36:37], v[4:5] op_sel_hi:[1,0]
	ds_write2_b32 v84, v96, v97 offset1:1
	v_mov_b32_e32 v96, v5
	v_pk_mul_f32 v[98:99], v[42:43], v[96:97] op_sel_hi:[1,0]
	v_pk_mul_f32 v[96:97], v[44:45], v[96:97] op_sel_hi:[1,0]
	ds_write2_b32 v86, v96, v97 offset1:1
	v_pk_mul_f32 v[96:97], v[50:51], v[6:7] op_sel_hi:[1,0]
	ds_write2_b32 v87, v96, v97 offset1:1
	v_pk_mul_f32 v[96:97], v[52:53], v[6:7] op_sel_hi:[1,0]
	ds_write2_b32 v88, v96, v97 offset1:1
	v_mov_b32_e32 v96, v7
	ds_write2_b32 v85, v98, v99 offset1:1
	v_pk_mul_f32 v[98:99], v[58:59], v[96:97] op_sel_hi:[1,0]
	v_pk_mul_f32 v[96:97], v[60:61], v[96:97] op_sel_hi:[1,0]
	ds_write2_b32 v90, v96, v97 offset1:1
	v_pk_mul_f32 v[96:97], v[66:67], v[8:9] op_sel_hi:[1,0]
	ds_write2_b32 v91, v96, v97 offset1:1
	v_pk_mul_f32 v[96:97], v[68:69], v[8:9] op_sel_hi:[1,0]
	ds_write2_b32 v92, v96, v97 offset1:1
	v_mov_b32_e32 v96, v9
	ds_write2_b32 v89, v98, v99 offset1:1
	v_pk_mul_f32 v[98:99], v[74:75], v[96:97] op_sel_hi:[1,0]
	v_pk_mul_f32 v[96:97], v[76:77], v[96:97] op_sel_hi:[1,0]
	ds_write2_b32 v93, v98, v99 offset1:1
	ds_write2_b32 v94, v96, v97 offset1:1
	s_waitcnt lgkmcnt(0)
	ds_read2_b32 v[160:161], v135 offset1:33
	ds_read2_b32 v[162:163], v135 offset0:66 offset1:99
	ds_read2_b32 v[164:165], v135 offset0:132 offset1:165
	ds_read2_b32 v[166:167], v135 offset0:198 offset1:231
	ds_read2_b32 v[168:169], v135 offset0:8 offset1:41
	ds_read2_b32 v[170:171], v135 offset0:74 offset1:107
	ds_read2_b32 v[172:173], v135 offset0:140 offset1:173
	ds_read2_b32 v[174:175], v135 offset0:206 offset1:239
	ds_read2_b32 v[176:177], v135 offset0:16 offset1:49
	ds_read2_b32 v[178:179], v135 offset0:82 offset1:115
	ds_read2_b32 v[180:181], v135 offset0:148 offset1:181
	ds_read2_b32 v[182:183], v135 offset0:214 offset1:247
	ds_read2_b32 v[184:185], v135 offset0:24 offset1:57
	ds_read2_b32 v[186:187], v135 offset0:90 offset1:123
	ds_read2_b32 v[188:189], v135 offset0:156 offset1:189
	ds_read2_b32 v[190:191], v135 offset0:222 offset1:255
	s_waitcnt lgkmcnt(15)
	v_cvt_pk_bf16_f32 v96, v160, v161
	s_waitcnt lgkmcnt(14)
	v_cvt_pk_bf16_f32 v97, v162, v163
	s_waitcnt lgkmcnt(13)
	v_cvt_pk_bf16_f32 v98, v164, v165
	v_add_u32_e32 v95, s29, v114
	s_waitcnt lgkmcnt(12)
	v_cvt_pk_bf16_f32 v99, v166, v167
	v_mad_i64_i32 v[100:101], s[4:5], s22, v95, 0
	s_ashr_i32 s27, s26, 31
	v_lshl_add_u64 v[100:101], v[100:101], 1, s[24:25]
	s_lshl_b64 s[4:5], s[26:27], 1
	v_lshl_add_u64 v[100:101], v[100:101], 0, s[4:5]
	v_lshl_add_u64 v[100:101], v[100:101], 0, v[118:119]
	global_store_dwordx4 v[100:101], v[96:99], off
	v_add_u32_e32 v95, s29, v128
	s_waitcnt lgkmcnt(11)
	v_cvt_pk_bf16_f32 v96, v168, v169
	s_waitcnt lgkmcnt(10)
	v_cvt_pk_bf16_f32 v97, v170, v171
	s_waitcnt lgkmcnt(9)
	v_cvt_pk_bf16_f32 v98, v172, v173
	s_waitcnt lgkmcnt(8)
	v_cvt_pk_bf16_f32 v99, v174, v175
	v_mad_i64_i32 v[100:101], s[8:9], s22, v95, 0
	v_lshl_add_u64 v[100:101], v[100:101], 1, s[24:25]
	v_lshl_add_u64 v[100:101], v[100:101], 0, s[4:5]
	v_lshl_add_u64 v[100:101], v[100:101], 0, v[118:119]
	global_store_dwordx4 v[100:101], v[96:99], off
	v_add_u32_e32 v95, s29, v129
	s_waitcnt lgkmcnt(7)
	v_cvt_pk_bf16_f32 v96, v176, v177
	s_waitcnt lgkmcnt(6)
	v_cvt_pk_bf16_f32 v97, v178, v179
	s_waitcnt lgkmcnt(5)
	v_cvt_pk_bf16_f32 v98, v180, v181
	s_waitcnt lgkmcnt(4)
	v_cvt_pk_bf16_f32 v99, v182, v183
	v_mad_i64_i32 v[100:101], s[8:9], s22, v95, 0
	v_lshl_add_u64 v[100:101], v[100:101], 1, s[24:25]
	v_lshl_add_u64 v[100:101], v[100:101], 0, s[4:5]
	v_lshl_add_u64 v[100:101], v[100:101], 0, v[118:119]
	global_store_dwordx4 v[100:101], v[96:99], off
	v_add_u32_e32 v95, s29, v130
	s_waitcnt lgkmcnt(3)
	v_cvt_pk_bf16_f32 v96, v184, v185
	s_waitcnt lgkmcnt(2)
	v_cvt_pk_bf16_f32 v97, v186, v187
	s_waitcnt lgkmcnt(1)
	v_cvt_pk_bf16_f32 v98, v188, v189
	s_waitcnt lgkmcnt(0)
	v_cvt_pk_bf16_f32 v99, v190, v191
	v_mad_i64_i32 v[100:101], s[8:9], s22, v95, 0
	v_lshl_add_u64 v[100:101], v[100:101], 1, s[24:25]
	v_lshl_add_u64 v[100:101], v[100:101], 0, s[4:5]
	v_lshl_add_u64 v[100:101], v[100:101], 0, v[118:119]
	global_store_dwordx4 v[100:101], v[96:99], off
	s_waitcnt lgkmcnt(0)
.LBB0_452:
	s_and_b64 vcc, exec, s[6:7]
	s_cbranch_vccnz .LBB0_361
	v_pk_mul_f32 v[96:97], v[22:23], v[10:11] op_sel_hi:[1,0]
	ds_write2_b32 v136, v96, v97 offset1:1
	v_pk_mul_f32 v[96:97], v[24:25], v[10:11] op_sel_hi:[1,0]
	ds_write2_b32 v136, v96, v97 offset0:2 offset1:3
	v_pk_mul_f32 v[96:97], v[30:31], v[10:11] op_sel:[0,1]
	ds_write2_b32 v1, v96, v97 offset1:1
	v_pk_mul_f32 v[96:97], v[32:33], v[10:11] op_sel:[0,1]
	ds_write2_b32 v82, v96, v97 offset1:1
	v_pk_mul_f32 v[96:97], v[38:39], v[12:13] op_sel_hi:[1,0]
	ds_write2_b32 v83, v96, v97 offset1:1
	v_pk_mul_f32 v[82:83], v[40:41], v[12:13] op_sel_hi:[1,0]
	ds_write2_b32 v84, v82, v83 offset1:1
	v_mov_b32_e32 v82, v13
	v_pk_mul_f32 v[96:97], v[46:47], v[82:83] op_sel_hi:[1,0]
	v_pk_mul_f32 v[82:83], v[48:49], v[82:83] op_sel_hi:[1,0]
	ds_write2_b32 v86, v82, v83 offset1:1
	v_pk_mul_f32 v[82:83], v[54:55], v[14:15] op_sel_hi:[1,0]
	ds_write2_b32 v87, v82, v83 offset1:1
	v_pk_mul_f32 v[82:83], v[56:57], v[14:15] op_sel_hi:[1,0]
	ds_write2_b32 v88, v82, v83 offset1:1
	v_mov_b32_e32 v82, v15
	ds_write2_b32 v85, v96, v97 offset1:1
	v_pk_mul_f32 v[84:85], v[62:63], v[82:83] op_sel_hi:[1,0]
	v_pk_mul_f32 v[82:83], v[64:65], v[82:83] op_sel_hi:[1,0]
	ds_write2_b32 v90, v82, v83 offset1:1
	v_pk_mul_f32 v[82:83], v[70:71], v[16:17] op_sel_hi:[1,0]
	ds_write2_b32 v91, v82, v83 offset1:1
	v_pk_mul_f32 v[82:83], v[72:73], v[16:17] op_sel_hi:[1,0]
	ds_write2_b32 v92, v82, v83 offset1:1
	v_mov_b32_e32 v82, v17
	ds_write2_b32 v89, v84, v85 offset1:1
	v_pk_mul_f32 v[84:85], v[78:79], v[82:83] op_sel_hi:[1,0]
	v_pk_mul_f32 v[82:83], v[80:81], v[82:83] op_sel_hi:[1,0]
	ds_write2_b32 v93, v84, v85 offset1:1
	ds_write2_b32 v94, v82, v83 offset1:1
	s_waitcnt lgkmcnt(0)
	ds_read2_b32 v[160:161], v135 offset1:33
	ds_read2_b32 v[162:163], v135 offset0:66 offset1:99
	ds_read2_b32 v[164:165], v135 offset0:132 offset1:165
	ds_read2_b32 v[166:167], v135 offset0:198 offset1:231
	ds_read2_b32 v[168:169], v135 offset0:8 offset1:41
	ds_read2_b32 v[170:171], v135 offset0:74 offset1:107
	ds_read2_b32 v[172:173], v135 offset0:140 offset1:173
	ds_read2_b32 v[174:175], v135 offset0:206 offset1:239
	ds_read2_b32 v[176:177], v135 offset0:16 offset1:49
	ds_read2_b32 v[178:179], v135 offset0:82 offset1:115
	ds_read2_b32 v[180:181], v135 offset0:148 offset1:181
	ds_read2_b32 v[182:183], v135 offset0:214 offset1:247
	ds_read2_b32 v[184:185], v135 offset0:24 offset1:57
	ds_read2_b32 v[186:187], v135 offset0:90 offset1:123
	ds_read2_b32 v[188:189], v135 offset0:156 offset1:189
	ds_read2_b32 v[190:191], v135 offset0:222 offset1:255
	s_waitcnt lgkmcnt(15)
	v_cvt_pk_bf16_f32 v82, v160, v161
	s_waitcnt lgkmcnt(14)
	v_cvt_pk_bf16_f32 v83, v162, v163
	s_waitcnt lgkmcnt(13)
	v_cvt_pk_bf16_f32 v84, v164, v165
	v_add_u32_e32 v1, s23, v114
	s_waitcnt lgkmcnt(12)
	v_cvt_pk_bf16_f32 v85, v166, v167
	v_mad_i64_i32 v[86:87], s[4:5], s2, v1, 0
	s_ashr_i32 s21, s20, 31
	v_lshl_add_u64 v[86:87], v[86:87], 1, s[18:19]
	s_lshl_b64 s[4:5], s[20:21], 1
	v_lshl_add_u64 v[86:87], v[86:87], 0, s[4:5]
	v_mov_b32_e32 v119, v117
	v_lshl_add_u64 v[86:87], v[86:87], 0, v[118:119]
	global_store_dwordx4 v[86:87], v[82:85], off
	v_add_u32_e32 v1, s23, v128
	s_waitcnt lgkmcnt(11)
	v_cvt_pk_bf16_f32 v82, v168, v169
	s_waitcnt lgkmcnt(10)
	v_cvt_pk_bf16_f32 v83, v170, v171
	s_waitcnt lgkmcnt(9)
	v_cvt_pk_bf16_f32 v84, v172, v173
	s_waitcnt lgkmcnt(8)
	v_cvt_pk_bf16_f32 v85, v174, v175
	v_mad_i64_i32 v[86:87], s[6:7], s2, v1, 0
	v_lshl_add_u64 v[86:87], v[86:87], 1, s[18:19]
	v_lshl_add_u64 v[86:87], v[86:87], 0, s[4:5]
	v_lshl_add_u64 v[86:87], v[86:87], 0, v[118:119]
	global_store_dwordx4 v[86:87], v[82:85], off
	v_add_u32_e32 v1, s23, v129
	s_waitcnt lgkmcnt(7)
	v_cvt_pk_bf16_f32 v82, v176, v177
	s_waitcnt lgkmcnt(6)
	v_cvt_pk_bf16_f32 v83, v178, v179
	s_waitcnt lgkmcnt(5)
	v_cvt_pk_bf16_f32 v84, v180, v181
	s_waitcnt lgkmcnt(4)
	v_cvt_pk_bf16_f32 v85, v182, v183
	v_mad_i64_i32 v[86:87], s[6:7], s2, v1, 0
	v_lshl_add_u64 v[86:87], v[86:87], 1, s[18:19]
	v_lshl_add_u64 v[86:87], v[86:87], 0, s[4:5]
	v_lshl_add_u64 v[86:87], v[86:87], 0, v[118:119]
	global_store_dwordx4 v[86:87], v[82:85], off
	v_add_u32_e32 v1, s23, v130
	s_waitcnt lgkmcnt(3)
	v_cvt_pk_bf16_f32 v82, v184, v185
	s_waitcnt lgkmcnt(2)
	v_cvt_pk_bf16_f32 v83, v186, v187
	s_waitcnt lgkmcnt(1)
	v_cvt_pk_bf16_f32 v84, v188, v189
	s_waitcnt lgkmcnt(0)
	v_cvt_pk_bf16_f32 v85, v190, v191
	v_mad_i64_i32 v[86:87], s[2:3], s2, v1, 0
	v_lshl_add_u64 v[86:87], v[86:87], 1, s[18:19]
	v_lshl_add_u64 v[86:87], v[86:87], 0, s[4:5]
	v_lshl_add_u64 v[86:87], v[86:87], 0, v[118:119]
	global_store_dwordx4 v[86:87], v[82:85], off
	s_waitcnt lgkmcnt(0)
	s_branch .LBB0_361
